# diff attention: K and V tiles staged by direct HBM->LDS loads (global_load_lds_dwordx4, source-side swizzle), replacing register staging + ds_write; on top of hand-written diff epilogue + in-proj ssq
# speedup vs baseline: 1.0082x; 1.0082x over previous
; __device__ __forceinline__ float max3f(float a, float b, float c) { float r; asm("v_max3_f32 %0, %1, %2, %3" : "=v"(r) : "v"(a), "v"(b), "v"(c)); return r; }
; #define SLOAD(i, k0) do { sr_[i].vs0 = ld8(&Vg[(long)((k0) + sr) * LDP + sc]); sr_[i].vs1 = ld8(&Vg[(long)((k0) + 32 + sr) * LDP + sc]); \
;     sr_[i].ks0 = ld8(&Kg[(long)((k0) + sr) * LDP + sc]); sr_[i].ks1 = ld8(&Kg[(long)((k0) + 32 + sr) * LDP + sc]); } while (0)
; #define SWRITE(off, i) do { *(bf16x8*)(V_lds + (off) + vst0) = sr_[i].vs0;          \
;     *(bf16x8*)(V_lds + (off) + vst1) = sr_[i].vs1; int kc = sc * 2;               \
;     *(bf16x8*)(K_lds + (off) + KSWZ(sr, kc)) = sr_[i].ks0;                       \
;     *(bf16x8*)(K_lds + (off) + KSWZ(32 + sr, kc)) = sr_[i].ks1; } while (0)
; #define SWAIT() asm volatile("s_waitcnt vmcnt(0)" ::: "memory")
; template <bool FIRST> __device__ __forceinline__ void partialSM2(f32x16& p0, f32x16& p1, float& m_ref, f32x16& negm, float& alpha) {
;   float pmax = max3f(p0[0], p0[1], p1[0]), pmb = max3f(p0[2], p0[3], p1[1]);
;   pmax = max3f(pmax, p1[2], p1[3]);
; #pragma unroll
;   for (int r = 4; r < 16; r += 4) { pmax = max3f(pmax, p0[r], p0[r + 1]); pmb = max3f(pmb, p0[r + 2], p0[r + 3]); pmax = max3f(pmax, p1[r], p1[r + 1]); pmb = max3f(pmb, p1[r + 2], p1[r + 3]); }
;   pmax = max3f(pmax, pmb, pmb);
;   { auto rr = __builtin_amdgcn_permlane32_swap(__float_as_uint(pmax), __float_as_uint(pmax), false, false);
;     pmax = fmaxf(__uint_as_float(rr[0]), __uint_as_float(rr[1])); }
;   alpha = 1.f;
;   if (FIRST || !__builtin_expect(__all(pmax <= THR), 1)) {
;     const float dl = FIRST ? pmax : fmaxf(pmax, 0.f); m_ref += dl; if (!FIRST) alpha = __builtin_amdgcn_exp2f(-dl);
; #pragma unroll
;     for (int r = 0; r < 16; ++r) { p0[r] -= dl; p1[r] -= dl; negm[r] -= dl; }
;   }
; #pragma unroll
;   for (int r = 0; r < 16; ++r) p0[r] = __builtin_amdgcn_exp2f(p0[r]);
; template <int MODE, int ORD> ...
;     ...
;   SETBE(0); qkt<ND0>(pA0, pA1, K_lds, qr, r32, hi, cboff, negm); BIAS(pA0, pA1, 0); partialSM2<MODE == 0>(pA0, pA1, m_reg, negm, alA);
;   SLOAD(SO, KVBLK);
;   SWAIT(); SWRITE(SLOT, SO); __syncthreads();
;   int op = 0, oc = SLOT, on = 2 * SLOT;
.LBB0_162:
	v_and_b32_e32 v1, 63, v40
	v_lshlrev_b32_e32 v35, 4, v1
	v_lshlrev_b32_e32 v34, 3, v1
	v_and_b32_e32 v35, 0xc0, v35
	v_lshlrev_b32_e32 v36, 1, v1
	v_and_or_b32 v35, v34, 24, v35
	v_and_b32_e32 v36, 32, v36
	v_and_b32_e32 v34, 0x100, v34
	s_cmp_lg_u32 0, -1
	v_or3_b32 v34, v35, v36, v34
	s_cselect_b32 s34, 0, 0
	v_add_u32_e32 v199, s34, v34
	v_max3_f32 v34, v18, v19, v2
	v_max3_f32 v35, v20, v21, v3
	v_cndmask_b32_e64 v214, 0, v46, s[0:1]
	v_max3_f32 v34, v34, v4, v5
	v_max3_f32 v35, v35, v24, v25
	s_and_b32 s0, s63, 0x3fffffc0
	v_max3_f32 v34, v34, v22, v23
	v_max3_f32 v35, v35, v8, v9
	s_lshl_b32 s0, s0, 2
	v_max3_f32 v34, v34, v6, v7
	v_max3_f32 v35, v35, v28, v29
	v_add_u32_e32 v36, 0x60, v38
	v_max3_f32 v34, v34, v26, v27
	s_add_i32 s49, s0, 0
	v_max3_f32 v58, v34, v10, v11
	v_add_u32_e32 v34, 64, v38
	v_max3_f32 v59, v35, v12, v13
	v_mad_i64_i32 v[34:35], s[0:1], v34, s73, 0
	v_mad_i64_i32 v[36:37], s[0:1], v36, s73, 0
	v_or_b32_e32 v34, v34, v41
	v_or_b32_e32 v36, v36, v41
	v_lshlrev_b64 v[50:51], 1, v[34:35]
	v_lshlrev_b64 v[52:53], 1, v[36:37]
	v_lshl_add_u64 v[34:35], s[42:43], 0, v[50:51]
	v_lshl_add_u64 v[46:47], s[42:43], 0, v[52:53]
	v_lshl_add_u64 v[50:51], s[18:19], 0, v[50:51]
	v_lshl_add_u64 v[54:55], s[18:19], 0, v[52:53]
	global_load_dwordx4 v[34:37], v[34:35], off
	s_nop 0
	global_load_dwordx4 v[46:49], v[46:47], off
	s_nop 0
	global_load_dwordx4 v[50:53], v[50:51], off offset:2048
	s_nop 0
	global_load_dwordx4 v[54:57], v[54:55], off offset:2048
	v_max3_f32 v41, v58, v30, v31
	v_max3_f32 v58, v59, v32, v33
	s_add_i32 s68, s68, s79
	v_max3_f32 v41, v41, v14, v15
	v_max3_f32 v58, v58, v16, v17
	v_ashrrev_i32_e32 v39, 31, v38
	v_max3_f32 v41, v41, v58, v58
	v_cmp_gt_u32_e64 s[0:1], 32, v1
	v_mov_b32_e32 v58, v41
	s_nop 1
	v_permlane32_swap_b32_e32 v41, v58
	v_max_f32_e32 v58, v58, v58
	v_max_f32_e32 v41, v41, v41
	v_max_f32_e32 v41, v41, v58
	v_sub_f32_e32 v64, v0, v41
	v_add_u32_e32 v0, s68, v184
	v_sub_f32_e32 v81, v3, v41
	v_sub_f32_e32 v80, v2, v41
	v_sub_u32_e32 v202, v197, v0
	v_lshl_add_u64 v[0:1], s[10:11], 0, v[38:39]
	v_mov_b32_e32 v2, s78
	v_mov_b32_e32 v3, v205
	v_mad_u64_u32 v[2:3], s[10:11], v0, s53, v[2:3]
	v_mov_b32_e32 v0, v3
	v_sub_f32_e32 v18, v18, v41
	v_sub_f32_e32 v19, v19, v41
	v_sub_f32_e32 v20, v20, v41
	v_sub_f32_e32 v21, v21, v41
	v_sub_f32_e32 v22, v22, v41
	v_sub_f32_e32 v23, v23, v41
	v_sub_f32_e32 v24, v24, v41
	v_sub_f32_e32 v25, v25, v41
	v_sub_f32_e32 v26, v26, v41
	v_sub_f32_e32 v27, v27, v41
	v_sub_f32_e32 v28, v28, v41
	v_sub_f32_e32 v29, v29, v41
	v_sub_f32_e32 v30, v30, v41
	v_sub_f32_e32 v31, v31, v41
	v_sub_f32_e32 v32, v32, v41
	v_sub_f32_e32 v33, v33, v41
	v_mad_u64_u32 v[0:1], s[10:11], v1, s53, v[0:1]
	v_exp_f32_e32 v173, v18
	v_exp_f32_e32 v175, v19
	v_exp_f32_e32 v171, v20
	v_exp_f32_e32 v174, v21
	v_exp_f32_e32 v169, v22
	v_exp_f32_e32 v172, v23
	v_exp_f32_e32 v168, v24
	v_exp_f32_e32 v170, v25
	v_exp_f32_e32 v165, v26
	v_exp_f32_e32 v167, v27
	v_exp_f32_e32 v163, v28
	v_exp_f32_e32 v166, v29
	v_exp_f32_e32 v161, v30
	v_exp_f32_e32 v164, v31
	v_exp_f32_e32 v160, v32
	v_exp_f32_e32 v162, v33
	v_and_b32_e32 v1, 15, v40
	v_readlane_b32 s10, v255, 31
	v_sub_f32_e32 v93, v15, v41
	v_sub_f32_e32 v92, v14, v41
	s_waitcnt vmcnt(0)
	v_lshl_or_b32 v2, v1, 4, v2
	v_mov_b32_e32 v3, v0
	v_readlane_b32 s11, v255, 32
	v_mov_b32_e32 v14, v205
	v_mov_b32_e32 v15, v205
	s_add_i32 s49, s49, 0x18000
	v_sub_f32_e32 v95, v17, v41
	v_sub_f32_e32 v94, v16, v41
	v_sub_f32_e32 v91, v13, v41
	v_sub_f32_e32 v90, v12, v41
	v_sub_f32_e32 v89, v11, v41
	v_sub_f32_e32 v88, v10, v41
	v_sub_f32_e32 v87, v9, v41
	v_sub_f32_e32 v86, v8, v41
	v_sub_f32_e32 v85, v7, v41
	v_sub_f32_e32 v84, v6, v41
	v_sub_f32_e32 v83, v5, v41
	v_sub_f32_e32 v82, v4, v41
	s_waitcnt vmcnt(3)
	ds_write_b128 v44, v[34:37] offset:32768
	s_waitcnt vmcnt(2)
	ds_write_b128 v45, v[46:49] offset:32768
	s_waitcnt vmcnt(1)
	ds_write_b128 v42, v[50:53] offset:49152
	s_waitcnt vmcnt(0)
	ds_write_b128 v43, v[54:57] offset:49152
	v_lshl_add_u64 v[176:177], s[10:11], 0, v[2:3]
	v_and_b32_e32 v240, 63, v244
	s_lshl_b32 s100, s62, 2
	s_and_b32 s101, s62, 1
	s_lshl_b32 s101, s101, 3
	v_lshrrev_b32_e32 v241, 4, v240
	v_or_b32_e32 v242, s101, v241
	v_and_b32_e32 v243, 15, v240
	v_xor_b32_e32 v242, v243, v242
	v_add_u32_e32 v245, s100, v241
	v_mul_u32_u24_e32 v245, 0x2400, v245
	v_lshl_add_u32 v234, v242, 4, v245
	v_xor_b32_e32 v242, 4, v242
	v_add_u32_e32 v245, 0x9000, v245
	v_lshl_add_u32 v235, v242, 4, v245
	v_bfe_u32 v241, v240, 2, 3
	s_lshl_b32 s101, s62, 3
	v_or_b32_e32 v241, s101, v241
	v_and_b32_e32 v242, 0xfffffff3, v241
	v_and_b32_e32 v243, 4, v241
	v_lshlrev_b32_e32 v243, 1, v243
	v_or_b32_e32 v242, v242, v243
	v_and_b32_e32 v243, 8, v241
	v_lshrrev_b32_e32 v243, 1, v243
	v_or_b32_e32 v242, v242, v243
	v_subrev_u32_e32 v242, s100, v242
	v_mul_u32_u24_e32 v242, 0x2400, v242
	v_lshrrev_b32_e32 v243, 5, v240
	v_lshlrev_b32_e32 v243, 6, v243
	v_and_b32_e32 v245, 3, v240
	v_lshl_add_u32 v243, v245, 4, v243
	v_add_u32_e32 v236, v242, v243
	v_add_u32_e32 v236, 0x800, v236
	v_add_u32_e32 v237, 0x80, v236
	v_readfirstlane_b32 s100, v176
	v_readfirstlane_b32 s101, v177
	v_mov_b32_e32 v0, v205
	v_mov_b32_e32 v1, v205
	v_mov_b32_e32 v2, v205
	v_mov_b32_e32 v3, v205
	v_mov_b32_e32 v4, v205
	v_mov_b32_e32 v5, v205
	v_mov_b32_e32 v6, v205
	v_mov_b32_e32 v7, v205
	v_mov_b32_e32 v8, v205
	v_mov_b32_e32 v9, v205
	v_mov_b32_e32 v10, v205
	v_mov_b32_e32 v11, v205
	v_mov_b32_e32 v12, v205
	v_mov_b32_e32 v13, v205
	v_mov_b64_e32 v[62:63], v[14:15]
	v_mov_b64_e32 v[46:47], v[14:15]
	v_mov_b64_e32 v[30:31], v[14:15]
	s_mov_b32 s56, 0
	s_mov_b32 s57, 2
	v_mov_b32_e32 v65, v64
	v_mov_b32_e32 v66, v64
	v_mov_b32_e32 v67, v64
	v_mov_b32_e32 v68, v64
	v_mov_b32_e32 v69, v64
	v_mov_b32_e32 v70, v64
	v_mov_b32_e32 v71, v64
	v_mov_b32_e32 v72, v64
	v_mov_b32_e32 v73, v64
	v_mov_b32_e32 v74, v64
	v_mov_b32_e32 v75, v64
	v_mov_b32_e32 v76, v64
	v_mov_b32_e32 v77, v64
	v_mov_b32_e32 v78, v64
	v_mov_b32_e32 v79, v64
	s_add_i32 s19, s92, 0x9f
	v_lshl_add_u32 v186, v184, 2, s49
	s_sub_i32 s42, 0, s68
	v_mov_b32_e32 v187, 0
	v_mov_b32_e32 v203, 1.0
	s_mov_b32 s18, 0x10000
	s_mov_b32 s43, 0x8000
	v_mov_b64_e32 v[60:61], v[12:13]
	v_mov_b64_e32 v[58:59], v[10:11]
	v_mov_b64_e32 v[56:57], v[8:9]
	v_mov_b64_e32 v[54:55], v[6:7]
	v_mov_b64_e32 v[52:53], v[4:5]
	v_mov_b64_e32 v[50:51], v[2:3]
	v_mov_b64_e32 v[48:49], v[0:1]
	v_mov_b64_e32 v[44:45], v[12:13]
	v_mov_b64_e32 v[42:43], v[10:11]
	v_mov_b64_e32 v[40:41], v[8:9]
	v_mov_b64_e32 v[38:39], v[6:7]
	v_mov_b64_e32 v[36:37], v[4:5]
	v_mov_b64_e32 v[34:35], v[2:3]
	v_mov_b64_e32 v[32:33], v[0:1]
	v_mov_b64_e32 v[28:29], v[12:13]
	v_mov_b64_e32 v[26:27], v[10:11]
	v_mov_b64_e32 v[24:25], v[8:9]
	v_mov_b64_e32 v[22:23], v[6:7]
	v_mov_b64_e32 v[20:21], v[4:5]
	v_mov_b64_e32 v[18:19], v[2:3]
	v_mov_b64_e32 v[16:17], v[0:1]
	s_mov_b32 s10, 0
	s_waitcnt lgkmcnt(0)
	s_barrier
; template <int MODE, int ORD> ...
;     ...
;   float bL, bR, be_cur = 0.f; f32x16 negm;
; #pragma unroll
;   for (int r = 0; r < 16; ++r) negm[r] = -m_reg;
.LBB0_163:
	s_mov_b32 s68, s43
	s_mov_b32 s43, s10
	s_lshl_b32 m0, s62, 11
	s_add_i32 m0, m0, s18
	s_nop 0
	global_load_lds_dwordx4 v236, s[100:101]
	s_addk_i32 m0, 0x400
	s_nop 0
	global_load_lds_dwordx4 v237, s[100:101]
	s_addk_i32 m0, 0x3c00
	s_nop 0
	global_load_lds_dwordx4 v234, s[100:101]
	s_addk_i32 m0, 0x400
	s_nop 0
	global_load_lds_dwordx4 v235, s[100:101]
	s_nop 0
	s_add_u32 s100, s100, 0x90000
	s_addc_u32 s101, s101, 0
	s_add_i32 s78, s42, s56
	s_add_i32 s34, s56, 64
	s_add_i32 s35, s78, 0x7f
	s_cmpk_gt_i32 s35, 0xff80
	s_cselect_b64 s[10:11], -1, 0
	s_cmp_lt_u32 s34, s19
	s_cselect_b64 s[80:81], -1, 0
	s_and_b64 s[10:11], s[10:11], s[80:81]
	s_cmpk_lt_i32 s35, 0xff81
	s_cselect_b64 vcc, -1, 0
	v_cndmask_b32_e32 v96, v200, v195, vcc
	v_cndmask_b32_e64 v215, v96, 0, s[10:11]
	v_cmp_eq_f32_e32 vcc, v215, v214
	s_cbranch_vccnz .LBB0_165
	v_sub_f32_e32 v96, v215, v214
	v_pk_add_f32 v[78:79], v[78:79], v[96:97] op_sel_hi:[1,0]
	v_pk_add_f32 v[76:77], v[76:77], v[96:97] op_sel_hi:[1,0]
	v_pk_add_f32 v[74:75], v[74:75], v[96:97] op_sel_hi:[1,0]
	v_pk_add_f32 v[72:73], v[72:73], v[96:97] op_sel_hi:[1,0]
	v_pk_add_f32 v[70:71], v[70:71], v[96:97] op_sel_hi:[1,0]
	v_pk_add_f32 v[68:69], v[68:69], v[96:97] op_sel_hi:[1,0]
	v_pk_add_f32 v[66:67], v[66:67], v[96:97] op_sel_hi:[1,0]
	v_pk_add_f32 v[64:65], v[64:65], v[96:97] op_sel_hi:[1,0]
	s_branch .LBB0_166

; #define SBAR() __builtin_amdgcn_sched_barrier(0)
; #define VRD8(D0, L0, H0, L1, H1, L2, H2, L3, H3) do { L0 = tr_read<v_rd_off(D0, 0, 0)>(vb); H0 = tr_read<v_rd_off(D0, 0, 1)>(vb); L1 = tr_read<v_rd_off(D0, 1, 0)>(vb); H1 = tr_read<v_rd_off(D0, 1, 1)>(vb); \
;     L2 = tr_read<v_rd_off(D0, 2, 0)>(vb); H2 = tr_read<v_rd_off(D0, 2, 1)>(vb); L3 = tr_read<v_rd_off(D0, 3, 0)>(vb); H3 = tr_read<v_rd_off(D0, 3, 1)>(vb); } while (0)
; #define MMA4(OD, L0, H0, L1, H1, L2, H2, L3, H3) do { OD = __builtin_amdgcn_mfma_f32_32x32x16_bf16(pa0, PK(L0, H0), OD, 0, 0, 0); OD = __builtin_amdgcn_mfma_f32_32x32x16_bf16(pa1, PK(L1, H1), OD, 0, 0, 0); \
;     OD = __builtin_amdgcn_mfma_f32_32x32x16_bf16(pa2, PK(L2, H2), OD, 0, 0, 0); OD = __builtin_amdgcn_mfma_f32_32x32x16_bf16(pa3, PK(L3, H3), OD, 0, 0, 0); } while (0)
; __device__ __forceinline__ void pv_partial(f32x16* o, int vb, bf16x8 pa0, bf16x8 pa1, bf16x8 pa2, bf16x8 pa3, f32x16& p0, f32x16& p1, float& m_ref, f32x16& negm, float& alpha) {
;     ...
;   VRD8(3, b0, b1, b2, b3, b4, b5, b6, b7);
;   asm volatile("s_waitcnt lgkmcnt(8)" ::: "memory"); SBAR();
;   MMA4(o[2], a0, a1, a2, a3, a4, a5, a6, a7);
; #pragma unroll
;   for (int r = 0; r < 8; ++r) p0[r] = __builtin_amdgcn_exp2f(p0[r]);
;   SBAR();
;   asm volatile("s_waitcnt lgkmcnt(0)" ::: "memory"); SBAR();
;   MMA4(o[3], b0, b1, b2, b3, b4, b5, b6, b7);
.LBB0_170:
	ds_read_b64_tr_b16 v[216:217], v201 offset:0x600
	ds_read_b64_tr_b16 v[218:219], v201 offset:0xe00
	ds_read_b64_tr_b16 v[220:221], v201 offset:0x1600
	ds_read_b64_tr_b16 v[222:223], v201 offset:0x1e00
	ds_read_b64_tr_b16 v[224:225], v201 offset:0x2600
	ds_read_b64_tr_b16 v[226:227], v201 offset:0x2e00
	ds_read_b64_tr_b16 v[228:229], v201 offset:0x3600
	ds_read_b64_tr_b16 v[230:231], v201 offset:0x3e00
	s_waitcnt lgkmcnt(8)
	v_mfma_f32_32x32x16_bf16 v[32:47], v[80:83], v[172:175], v[32:47]
	v_mfma_f32_32x32x16_bf16 v[32:47], v[88:91], v[168:171], v[32:47]
	v_mfma_f32_32x32x16_bf16 v[32:47], v[84:87], v[164:167], v[32:47]
	v_mfma_f32_32x32x16_bf16 v[32:47], v[92:95], v[160:163], v[32:47]
	s_waitcnt lgkmcnt(0)
	v_mfma_f32_32x32x16_bf16 v[16:31], v[80:83], v[216:219], v[16:31]
	s_add_i32 s79, s18, 0
	v_mfma_f32_32x32x16_bf16 v[16:31], v[88:91], v[220:223], v[16:31]
	v_cmp_gt_f32_e32 vcc, 1.0, v213
	v_mfma_f32_32x32x16_bf16 v[16:31], v[84:87], v[224:227], v[16:31]
	v_mfma_f32_32x32x16_bf16 v[16:31], v[92:95], v[228:231], v[16:31]
	s_cbranch_vccz .LBB0_174
	s_and_saveexec_b64 s[10:11], s[0:1]
	ds_write_b32 v186, v213 offset:128
	s_or_b64 exec, exec, s[10:11]
	s_waitcnt lgkmcnt(0)
	v_add_u32_e32 v92, s49, v204
	ds_read_b128 v[80:83], v92 offset:224
	ds_read_b128 v[84:87], v92 offset:192
	ds_read_b128 v[88:91], v92 offset:160
	ds_read_b128 v[92:95], v92 offset:128
	s_waitcnt lgkmcnt(3)
	v_pk_mul_f32 v[12:13], v[12:13], v[80:81]
	s_waitcnt lgkmcnt(2)
	v_pk_mul_f32 v[8:9], v[8:9], v[84:85]
	s_waitcnt lgkmcnt(1)
	v_pk_mul_f32 v[4:5], v[4:5], v[88:89]
	v_pk_mul_f32 v[14:15], v[14:15], v[82:83]
	v_pk_mul_f32 v[10:11], v[10:11], v[86:87]
	v_pk_mul_f32 v[6:7], v[6:7], v[90:91]
	s_waitcnt lgkmcnt(0)
	v_pk_mul_f32 v[2:3], v[2:3], v[94:95]
	v_pk_mul_f32 v[0:1], v[0:1], v[92:93]
	v_pk_mul_f32 v[60:61], v[60:61], v[80:81]
	v_pk_mul_f32 v[56:57], v[56:57], v[84:85]
	v_pk_mul_f32 v[52:53], v[52:53], v[88:89]
	v_pk_mul_f32 v[62:63], v[62:63], v[82:83]
	v_pk_mul_f32 v[58:59], v[58:59], v[86:87]
	v_pk_mul_f32 v[54:55], v[54:55], v[90:91]
	v_pk_mul_f32 v[50:51], v[50:51], v[94:95]
	v_pk_mul_f32 v[48:49], v[48:49], v[92:93]
	v_pk_mul_f32 v[44:45], v[44:45], v[80:81]
	v_pk_mul_f32 v[40:41], v[40:41], v[84:85]
	v_pk_mul_f32 v[36:37], v[36:37], v[88:89]
	v_pk_mul_f32 v[46:47], v[46:47], v[82:83]
	v_pk_mul_f32 v[42:43], v[42:43], v[86:87]
	v_pk_mul_f32 v[38:39], v[38:39], v[90:91]
	v_pk_mul_f32 v[34:35], v[34:35], v[94:95]
	v_pk_mul_f32 v[32:33], v[32:33], v[92:93]
	v_pk_mul_f32 v[28:29], v[28:29], v[80:81]
	v_pk_mul_f32 v[24:25], v[24:25], v[84:85]
	v_pk_mul_f32 v[20:21], v[20:21], v[88:89]
	v_pk_mul_f32 v[30:31], v[30:31], v[82:83]
	v_pk_mul_f32 v[26:27], v[26:27], v[86:87]
	v_pk_mul_f32 v[22:23], v[22:23], v[90:91]
	v_pk_mul_f32 v[18:19], v[18:19], v[94:95]
	v_pk_mul_f32 v[16:17], v[16:17], v[92:93]
.LBB0_174:
	s_addk_i32 s56, 0x80
	s_waitcnt vmcnt(0)
	s_waitcnt lgkmcnt(0)
	s_barrier
	s_lshl_b32 m0, s62, 11
	s_add_i32 m0, m0, s43
	s_nop 0
	global_load_lds_dwordx4 v236, s[100:101]
	s_addk_i32 m0, 0x400
	s_nop 0
	global_load_lds_dwordx4 v237, s[100:101]
	s_addk_i32 m0, 0x3c00
	s_nop 0
	global_load_lds_dwordx4 v234, s[100:101]
	s_addk_i32 m0, 0x400
	s_nop 0
	global_load_lds_dwordx4 v235, s[100:101]
	s_nop 0
	s_add_u32 s100, s100, 0x90000
	s_addc_u32 s101, s101, 0
	s_addk_i32 s78, 0xbf
	s_cmpk_gt_i32 s78, 0xff80
	s_cselect_b64 s[10:11], -1, 0
	s_cmp_lt_u32 s56, s19
	s_cselect_b64 s[80:81], -1, 0
	s_and_b64 s[10:11], s[10:11], s[80:81]
	s_cmpk_lt_i32 s78, 0xff81
	s_cselect_b64 vcc, -1, 0
	v_cndmask_b32_e32 v80, v200, v195, vcc
	v_cndmask_b32_e64 v214, v80, 0, s[10:11]
	v_cmp_eq_f32_e32 vcc, v214, v215
	s_cbranch_vccnz .LBB0_176
	v_sub_f32_e32 v80, v214, v215
	v_pk_add_f32 v[78:79], v[80:81], v[78:79] op_sel_hi:[0,1]
	v_pk_add_f32 v[76:77], v[80:81], v[76:77] op_sel_hi:[0,1]
	v_pk_add_f32 v[74:75], v[80:81], v[74:75] op_sel_hi:[0,1]
	v_pk_add_f32 v[72:73], v[80:81], v[72:73] op_sel_hi:[0,1]
	v_pk_add_f32 v[70:71], v[80:81], v[70:71] op_sel_hi:[0,1]
	v_pk_add_f32 v[68:69], v[80:81], v[68:69] op_sel_hi:[0,1]
	v_pk_add_f32 v[66:67], v[80:81], v[66:67] op_sel_hi:[0,1]
	v_pk_add_f32 v[64:65], v[80:81], v[64:65] op_sel_hi:[0,1]
	s_branch .LBB0_177

; #define SBAR() __builtin_amdgcn_sched_barrier(0)
; #define VRD8(D0, L0, H0, L1, H1, L2, H2, L3, H3) do { L0 = tr_read<v_rd_off(D0, 0, 0)>(vb); H0 = tr_read<v_rd_off(D0, 0, 1)>(vb); L1 = tr_read<v_rd_off(D0, 1, 0)>(vb); H1 = tr_read<v_rd_off(D0, 1, 1)>(vb); \
;     L2 = tr_read<v_rd_off(D0, 2, 0)>(vb); H2 = tr_read<v_rd_off(D0, 2, 1)>(vb); L3 = tr_read<v_rd_off(D0, 3, 0)>(vb); H3 = tr_read<v_rd_off(D0, 3, 1)>(vb); } while (0)
; #define MMA4(OD, L0, H0, L1, H1, L2, H2, L3, H3) do { OD = __builtin_amdgcn_mfma_f32_32x32x16_bf16(pa0, PK(L0, H0), OD, 0, 0, 0); OD = __builtin_amdgcn_mfma_f32_32x32x16_bf16(pa1, PK(L1, H1), OD, 0, 0, 0); \
;     OD = __builtin_amdgcn_mfma_f32_32x32x16_bf16(pa2, PK(L2, H2), OD, 0, 0, 0); OD = __builtin_amdgcn_mfma_f32_32x32x16_bf16(pa3, PK(L3, H3), OD, 0, 0, 0); } while (0)
; __device__ __forceinline__ void pv_partial(f32x16* o, int vb, bf16x8 pa0, bf16x8 pa1, bf16x8 pa2, bf16x8 pa3, f32x16& p0, f32x16& p1, float& m_ref, f32x16& negm, float& alpha) {
;     ...
;   VRD8(3, b0, b1, b2, b3, b4, b5, b6, b7);
;   asm volatile("s_waitcnt lgkmcnt(8)" ::: "memory"); SBAR();
;   MMA4(o[2], a0, a1, a2, a3, a4, a5, a6, a7);
; #pragma unroll
;   for (int r = 0; r < 8; ++r) p0[r] = __builtin_amdgcn_exp2f(p0[r]);
;   SBAR();
;   asm volatile("s_waitcnt lgkmcnt(0)" ::: "memory"); SBAR();
;   MMA4(o[3], b0, b1, b2, b3, b4, b5, b6, b7);
.LBB0_181:
	ds_read_b64_tr_b16 v[218:219], v217 offset:0x600
	ds_read_b64_tr_b16 v[220:221], v217 offset:0xe00
	ds_read_b64_tr_b16 v[222:223], v217 offset:0x1600
	ds_read_b64_tr_b16 v[224:225], v217 offset:0x1e00
	ds_read_b64_tr_b16 v[226:227], v217 offset:0x2600
	ds_read_b64_tr_b16 v[228:229], v217 offset:0x2e00
	ds_read_b64_tr_b16 v[230:231], v217 offset:0x3600
	ds_read_b64_tr_b16 v[232:233], v217 offset:0x3e00
	s_waitcnt lgkmcnt(8)
	v_mfma_f32_32x32x16_bf16 v[32:47], v[104:107], v[172:175], v[32:47]
	v_mfma_f32_32x32x16_bf16 v[32:47], v[108:111], v[168:171], v[32:47]
	v_mfma_f32_32x32x16_bf16 v[32:47], v[96:99], v[164:167], v[32:47]
	v_mfma_f32_32x32x16_bf16 v[32:47], v[100:103], v[160:163], v[32:47]
	s_waitcnt lgkmcnt(0)
	v_mfma_f32_32x32x16_bf16 v[16:31], v[104:107], v[218:221], v[16:31]
	s_add_i32 s78, s43, 0
	v_cmp_gt_f32_e32 vcc, 1.0, v212
	v_mfma_f32_32x32x16_bf16 v[16:31], v[108:111], v[222:225], v[16:31]
	v_mfma_f32_32x32x16_bf16 v[16:31], v[96:99], v[226:229], v[16:31]
	v_mfma_f32_32x32x16_bf16 v[16:31], v[100:103], v[230:233], v[16:31]
	s_cbranch_vccz .LBB0_185
	s_and_saveexec_b64 s[10:11], s[0:1]
	ds_write_b32 v186, v212 offset:128
	s_or_b64 exec, exec, s[10:11]
	s_waitcnt lgkmcnt(0)
	v_add_u32_e32 v108, s49, v204
	ds_read_b128 v[96:99], v108 offset:224
	ds_read_b128 v[100:103], v108 offset:192
	ds_read_b128 v[104:107], v108 offset:160
	ds_read_b128 v[108:111], v108 offset:128
	s_waitcnt lgkmcnt(3)
	v_pk_mul_f32 v[12:13], v[12:13], v[96:97]
	s_waitcnt lgkmcnt(2)
	v_pk_mul_f32 v[8:9], v[8:9], v[100:101]
	s_waitcnt lgkmcnt(1)
	v_pk_mul_f32 v[4:5], v[4:5], v[104:105]
	v_pk_mul_f32 v[14:15], v[14:15], v[98:99]
	v_pk_mul_f32 v[10:11], v[10:11], v[102:103]
	v_pk_mul_f32 v[6:7], v[6:7], v[106:107]
	s_waitcnt lgkmcnt(0)
	v_pk_mul_f32 v[2:3], v[2:3], v[110:111]
	v_pk_mul_f32 v[0:1], v[0:1], v[108:109]
	v_pk_mul_f32 v[60:61], v[60:61], v[96:97]
	v_pk_mul_f32 v[56:57], v[56:57], v[100:101]
	v_pk_mul_f32 v[52:53], v[52:53], v[104:105]
	v_pk_mul_f32 v[62:63], v[62:63], v[98:99]
	v_pk_mul_f32 v[58:59], v[58:59], v[102:103]
	v_pk_mul_f32 v[54:55], v[54:55], v[106:107]
	v_pk_mul_f32 v[50:51], v[50:51], v[110:111]
	v_pk_mul_f32 v[48:49], v[48:49], v[108:109]
	v_pk_mul_f32 v[44:45], v[44:45], v[96:97]
	v_pk_mul_f32 v[40:41], v[40:41], v[100:101]
	v_pk_mul_f32 v[36:37], v[36:37], v[104:105]
	v_pk_mul_f32 v[46:47], v[46:47], v[98:99]
	v_pk_mul_f32 v[42:43], v[42:43], v[102:103]
	v_pk_mul_f32 v[38:39], v[38:39], v[106:107]
	v_pk_mul_f32 v[34:35], v[34:35], v[110:111]
	v_pk_mul_f32 v[32:33], v[32:33], v[108:109]
	v_pk_mul_f32 v[28:29], v[28:29], v[96:97]
	v_pk_mul_f32 v[24:25], v[24:25], v[100:101]
	v_pk_mul_f32 v[20:21], v[20:21], v[104:105]
	v_pk_mul_f32 v[30:31], v[30:31], v[98:99]
	v_pk_mul_f32 v[26:27], v[26:27], v[102:103]
	v_pk_mul_f32 v[22:23], v[22:23], v[106:107]
	v_pk_mul_f32 v[18:19], v[18:19], v[110:111]
	v_pk_mul_f32 v[16:17], v[16:17], v[108:109]
.LBB0_185:
	v_exp_f32_e32 v173, v112
	v_exp_f32_e32 v175, v113
	v_exp_f32_e32 v171, v114
	v_exp_f32_e32 v174, v115
	v_exp_f32_e32 v169, v116
	v_exp_f32_e32 v172, v117
	v_exp_f32_e32 v168, v118
	v_exp_f32_e32 v170, v119
	v_exp_f32_e32 v165, v120
	v_exp_f32_e32 v167, v121
	v_exp_f32_e32 v163, v122
	v_exp_f32_e32 v166, v123
	v_exp_f32_e32 v161, v124
	v_exp_f32_e32 v164, v125
	v_exp_f32_e32 v160, v126
	v_exp_f32_e32 v162, v127
	v_add_f32_e32 v96, v210, v211
	v_fmac_f32_e32 v96, v203, v187
	v_add_f32_e32 v187, v215, v216
	s_add_i32 s57, s57, 2
	s_mov_b64 s[10:11], 0x120000
	v_fmac_f32_e32 v187, v96, v213
	s_cmp_ge_u32 s57, s67
	v_lshl_add_u64 v[176:177], v[176:177], 0, s[10:11]
	s_waitcnt vmcnt(0)
	s_waitcnt lgkmcnt(0)
	s_barrier
	s_cbranch_scc1 .LBB0_189
	s_mov_b32 s10, s18
	s_mov_b32 s18, s68
	v_mov_b32_e32 v203, v212
	s_branch .LBB0_163
